# end of the W_in GEMM: the drain before the forget-gate pass waits for the LDS-DMA ring only (counted wait), the last epilogue's 16 write-through stores stay in flight beside the forget-gate loads
# speedup vs baseline: 1.0027x; 1.0027x over previous
; #define PG8_WAIT_V(n) asm volatile("s_waitcnt vmcnt(" #n ")" ::: "memory")
; #define PG8_BAR __builtin_amdgcn_s_barrier()
; template <class Epi, class Sched, bool ALIGN_EPI = false, bool SP2 = false>
; __device__ __forceinline__ void gemm_phase(PG8_LAS unsigned char* lds, const Gemm g, const Sched& S, const Epi& E, const int tid) {
;     ...
;     PG8_WAIT_V(0);
;     if constexpr (!ALIGN_EPI) { if (wr == 0) PG8_BAR; }
;     PG8_BAR;
.LBB0_479:
	s_waitcnt vmcnt(16)
	v_readlane_b32 s60, v251, 40
	v_readlane_b32 s74, v251, 54
	v_readlane_b32 s75, v251, 55
	s_mov_b32 s27, 0x12000
	s_barrier
	v_readlane_b32 s61, v251, 41
	v_readlane_b32 s62, v251, 42
	v_readlane_b32 s63, v251, 43
	v_readlane_b32 s64, v251, 44
	v_readlane_b32 s65, v251, 45
	v_readlane_b32 s66, v251, 46
	v_readlane_b32 s67, v251, 47
	v_readlane_b32 s68, v251, 48
	v_readlane_b32 s69, v251, 49
	v_readlane_b32 s70, v251, 50
	v_readlane_b32 s71, v251, 51
	v_readlane_b32 s72, v251, 52
	v_readlane_b32 s73, v251, 53
	s_branch .Lfg_go

; #define LAS __attribute__((address_space(3)))
; __device__ __forceinline__ void fg_tail(const Args& a, int l, LAS unsigned char* lds, const int tid) {
;     const int lane = tid & 63, wid = tid >> 6;
;     unsigned char* ws = a.ws;
;     LAS f32x4* wl = (LAS f32x4*)lds;
;     {
;         const f32x4* wsrc = (const f32x4*)((const float*)(ws + WS_WFGT) + (size_t)l * 8192);
; #pragma unroll
;         for (int i = 0; i < 4; ++i) { const int idx = tid + 512 * i, j = idx >> 8, k4 = idx & 255, ln = k4 >> 2, q = k4 & 3; wl[(j * 4 + q) * 64 + ln] = wsrc[idx]; }
;     }
;     __syncthreads();
;     const bf16_t* H = (const bf16_t*)(ws + WS_H); const float* rowss = (const float*)(ws + WS_ROWSS) + (size_t)(2 * l) * MT * 4;
;     const float* mod = (const float*)(ws + WS_MOD) + (size_t)l * 8 * MODW; float* logf = (float*)(ws + WS_LOGF);
;     const float bfv = a.in[7][l * 8 + (lane >> 3)];
.Lfg_go:
	v_readlane_b32 s0, v252, 24
	v_lshlrev_b32_e32 v0, 10, v188
	v_lshlrev_b32_e32 v2, 2, v188
	v_ashrrev_i32_e32 v189, 31, v188
	v_readlane_b32 s1, v252, 25
	v_and_b32_e32 v0, 0xc00, v0
	v_and_b32_e32 v2, 0x3f0, v2
	s_waitcnt lgkmcnt(0)
	v_lshl_add_u64 v[190:191], v[188:189], 4, s[0:1]
	v_add3_u32 v0, 0, v0, v2
	v_and_b32_e32 v18, 0xfffff00, v188
	v_lshl_add_u32 v209, v18, 4, v0
	v_add_u32_e32 v18, 0x200, v188
	v_and_b32_e32 v18, 0xfffff00, v18
	v_lshl_add_u32 v210, v18, 4, v0
	v_add_u32_e32 v18, 0x400, v188
	v_and_b32_e32 v18, 0xfffff00, v18
	v_lshl_add_u32 v211, v18, 4, v0
	v_add_u32_e32 v18, 0x600, v188
	v_and_b32_e32 v18, 0xfffff00, v18
	v_lshl_add_u32 v213, v18, 4, v0
	v_readlane_b32 s0, v252, 26
	v_ashrrev_i32_e32 v0, 6, v188
	v_mov_b32_e32 v212, v248
	v_and_b32_e32 v208, 63, v188
	v_bfe_u32 v2, v188, 3, 3
	v_or_b32_e32 v2, s0, v2
	v_readlane_b32 s0, v249, 3
	v_ashrrev_i32_e32 v3, 31, v2
	v_lshl_add_u64 v[192:193], v[2:3], 2, s[74:75]
	v_readlane_b32 s1, v251, 11
	s_cmp_lg_u32 s1, 0x4000
	s_cbranch_scc1 .Lfg_nomap
	s_lshr_b32 s1, s0, 3
	s_and_b32 s0, s1, 7
	s_lshl_b32 s0, s0, 8
	s_andn2_b32 s1, s1, 7
	s_add_i32 s0, s0, s1
